# attention item rebalance (r2 swap for blk 32-63/192-223) + no grid barrier between phase 13 and 14
# speedup vs baseline: 1.0056x; 1.0056x over previous
; __device__ __forceinline__ void convert_layer(ArgsP a, LAS unsigned char* lds, int L) {
;     ...
;     const int gw = blockIdx.x * 8 + wave, NGW = gridDim.x * 8;
;     unsigned char* ws = a->ws;
;     const size_t oFF = (size_t)L * DM * DFF, oDD = (size_t)L * DM * DM;
;     constexpr int I_FF = (DM / 64) * (DFF / 64);
;     constexpr int NITEMS = 6 * I_FF + 32 * 44 + 32 * 36 + 2 * (32 * 32) + 4 * 32 + 16;
;     for (int it0 = gw; it0 < NITEMS; it0 += NGW) {
; __device__ __forceinline__ void attn_phase(ArgsP a, LAS unsigned char* lds, int L) {
;     ...
;     const int blk = blockIdx.x, G = gridDim.x;
;     const int nrounds = (G == 256) ? 3 : (768 + G - 1) / G;
;     for (int r = 0; r < nrounds; ++r) {
;         const int e = (G == 256) ? ((r == 0) ? blk : (r == 1 ? 511 - blk : 512 + (blk ^ 1))) : (blk + r * G);
;         if (e >= 768) break;
;         const int qt = 7 - e / 96, rest = e % 96, moba = rest & 1, bh = rest >> 1;
;         att::attn_item(lds, Z, Y, logf, ksum, a->in[2], moba, bh / 6, bh % 6, qt);
;     }
;     for (int pi = blk; pi < 256; pi += G) att::pool_item(lds, Z, Y, (const bf16_t*)(a->ws + WS_PW), a->in[13] + (size_t)L * 512, pi >> 2, pi & 3);
.LBB0_13:
	s_mul_i32 s0, s27, s26
	s_lshl_b32 s11, s2, 3
	s_lshl_b32 s28, s26, 3
	s_lshl_b32 s27, s26, 4
	s_cmpk_lt_i32 s2, 0x200
	s_cselect_b64 s[4:5], -1, 0
	s_ashr_i32 s33, s2, 31
	s_lshr_b32 s1, s33, 29
	s_add_i32 s1, s2, s1
	s_ashr_i32 s3, s1, 3
	s_and_b32 s1, s1, -8
	v_writelane_b32 v255, s4, 4
	s_sub_i32 s1, s2, s1
	s_ashr_i32 s67, s26, 31
	v_writelane_b32 v255, s5, 5
	s_lshl_b32 s4, s1, 6
	s_cmpk_lg_i32 s26, 0x100
	s_cselect_b64 s[6:7], -1, 0
	v_writelane_b32 v255, s6, 6
	s_add_i32 s5, s26, 0x2ff
	s_movk_i32 s51, 0x161
	v_writelane_b32 v255, s7, 7
	s_sub_i32 s6, 0x1ff, s2
	v_writelane_b32 v255, s6, 8
	s_lshr_b32 s7, s2, 5
	s_mov_b32 s6, s2
	s_cmp_eq_u32 s7, 1
	s_cselect_b32 s8, 0xa0, 0
	s_add_i32 s6, s6, s8
	s_cmp_eq_u32 s7, 6
	s_cselect_b32 s8, 0xa0, 0
	s_sub_i32 s6, s6, s8
	s_xor_b32 s6, s6, 1
	s_addk_i32 s6, 0x200
	s_cmpk_lt_i32 s2, 0x100
	v_writelane_b32 v255, s6, 9
	s_cselect_b64 s[6:7], -1, 0
	v_writelane_b32 v255, s6, 10
	s_cmpk_lt_i32 s2, 0x500
	v_lshrrev_b32_e32 v1, 20, v0
	v_writelane_b32 v255, s7, 11
	s_cselect_b64 s[6:7], -1, 0
	v_writelane_b32 v255, s6, 12
	s_cmp_lt_i32 s1, 0
	s_cselect_b32 s8, s51, 0x160
	v_writelane_b32 v255, s7, 13
	s_movk_i32 s7, 0xa1
	s_cselect_b32 s7, s7, 0xa0
	s_mul_i32 s6, s1, 0x41
	s_mul_i32 s7, s7, s1
	s_cselect_b32 s4, s6, s4
	s_add_i32 s7, s7, s3
	s_mul_hi_i32 s6, s7, 0x66666667
	s_lshr_b32 s9, s6, 31
	s_ashr_i32 s6, s6, 6
	s_add_i32 s6, s6, s9
	s_mul_i32 s9, s6, 0xa0
	s_sub_i32 s7, s7, s9
	s_bfe_u32 s9, s7, 0x3001c
	s_add_i32 s9, s7, s9
	s_sext_i32_i16 s10, s9
	s_and_b32 s9, s9, 0xfff8
	s_sub_i32 s7, s7, s9
	s_lshl_b32 s6, s6, 3
	s_sext_i32_i16 s7, s7
	s_add_i32 s6, s6, s7
	v_writelane_b32 v255, s6, 14
	s_ashr_i32 s6, s10, 3
	s_cmpk_lt_i32 s2, 0xb00
	v_writelane_b32 v255, s6, 15
	s_cselect_b64 s[6:7], -1, 0
	s_mul_i32 s1, s8, s1
	v_writelane_b32 v255, s6, 16
	s_add_i32 s1, s1, s3
	v_lshrrev_b32_e32 v0, 10, v0
	v_writelane_b32 v255, s7, 17
	s_mul_hi_i32 s6, s1, 0x2e8ba2e9
	s_lshr_b32 s7, s6, 31
	s_ashr_i32 s6, s6, 6
	s_add_i32 s6, s6, s7
	s_mul_i32 s7, s6, 0x160
	s_sub_i32 s1, s1, s7
	s_bfe_u32 s7, s1, 0x3001c
	s_add_i32 s7, s1, s7
	s_sext_i32_i16 s8, s7
	s_and_b32 s7, s7, 0xfff8
	s_sub_i32 s1, s1, s7
	s_lshl_b32 s6, s6, 3
	s_sext_i32_i16 s1, s1
	s_add_i32 s1, s6, s1
	v_writelane_b32 v255, s1, 18
	v_or_b32_e32 v0, v0, v1
	v_readlane_b32 s6, v255, 0
	v_readlane_b32 s7, v255, 1
	s_load_dword s1, s[6:7], 0xe0
	s_ashr_i32 s6, s8, 3
	v_writelane_b32 v255, s6, 19
	s_lshl_b32 s6, s2, 9
	v_writelane_b32 v255, s6, 20
	s_waitcnt lgkmcnt(0)
	s_mul_i32 s0, s0, s1
	v_writelane_b32 v255, s0, 21
	s_movk_i32 s0, 0x3ff
	v_and_or_b32 v1, v0, s0, v219
	s_add_i32 s0, s4, s3
	s_ashr_i32 s1, s0, 31
	s_lshr_b32 s1, s1, 27
	s_add_i32 s1, s0, s1
	s_ashr_i32 s3, s1, 5
	s_and_b32 s1, s1, 0xffe0
	s_sub_i32 s1, s0, s1
	s_bfe_i32 s0, s1, 0x80000
	s_bfe_u32 s0, s0, 0x2000d
	s_add_i32 s4, s1, s0
	s_bfe_i32 s0, s4, 0x80000
	s_and_b32 s4, s4, 0xfc
	s_sub_i32 s1, s1, s4
	s_abs_i32 s4, s26
	v_cvt_f32_u32_e32 v0, s4
	s_lshl_b32 s3, s3, 2
	s_sext_i32_i8 s1, s1
	s_sext_i32_i16 s6, s0
	v_rcp_iflag_f32_e32 v0, v0
	s_add_i32 s1, s3, s1
	s_lshr_b32 s0, s6, 2
	v_writelane_b32 v255, s1, 22
	v_mul_f32_e32 v0, 0x4f7ffffe, v0
	v_cvt_u32_f32_e32 v0, v0
	s_ashr_i32 s1, s6, 2
	v_writelane_b32 v255, s1, 23
	s_bfe_i64 s[0:1], s[0:1], 0x100000
	v_writelane_b32 v255, s0, 24
	s_sub_i32 s3, 0, s4
	s_lshl_b32 s40, s26, 9
	v_writelane_b32 v255, s1, 25
	s_xor_b32 s0, s5, s26
	s_abs_i32 s1, s5
	v_readfirstlane_b32 s5, v0
	s_mul_i32 s3, s3, s5
	s_mul_hi_u32 s3, s5, s3
	s_add_i32 s5, s5, s3
	s_mul_hi_u32 s3, s1, s5
	s_mul_i32 s5, s3, s4
	s_sub_i32 s1, s1, s5
	s_ashr_i32 s29, s28, 31
	s_ashr_i32 s0, s0, 31
	s_add_i32 s5, s3, 1
	s_sub_i32 s6, s1, s4
	s_cmp_ge_u32 s1, s4
	s_cselect_b32 s3, s5, s3
	s_cselect_b32 s1, s6, s1
	s_add_i32 s5, s3, 1
	s_cmp_ge_u32 s1, s4
	s_cselect_b32 s1, s5, s3
	s_xor_b32 s1, s1, s0
	s_sub_i32 s0, s1, s0
	v_writelane_b32 v255, s0, 26
	s_lshl_b32 s0, s2, 6
	v_writelane_b32 v255, s0, 27
	s_lshl_b32 s0, s26, 6
	v_writelane_b32 v255, s0, 28
	v_writelane_b32 v255, s11, 29
	s_add_i32 s0, s11, s28
	v_writelane_b32 v255, s0, 30
	s_add_i32 s0, 0, 0x19800
	v_writelane_b32 v255, s0, 31
	s_add_i32 s0, 0, 0x1aa24
	v_writelane_b32 v255, s0, 32
	s_add_i32 s0, 0, 0x1aa28
	v_writelane_b32 v255, s0, 33
	s_add_i32 s0, 0, 0x1aa2c
	v_writelane_b32 v255, s0, 34
	s_add_i32 s0, 0, 0x1aa30
	v_writelane_b32 v255, s0, 35
	s_add_i32 s0, 0, 0x1aa34
	v_writelane_b32 v255, s0, 36
	s_add_i32 s0, 0, 0x1aa38
	v_writelane_b32 v255, s0, 37
	s_add_i32 s0, 0, 0x1aa3c
	v_writelane_b32 v255, s0, 38
	s_add_i32 s0, 0, 0x1aa00
	v_writelane_b32 v255, s0, 39
	s_add_i32 s0, 0, 0x17900
	v_writelane_b32 v255, s0, 40
	s_add_i32 s0, 0, 0x11000
	v_writelane_b32 v255, s0, 41
	s_add_i32 s3, 0, 0x23fc0
	v_writelane_b32 v255, s3, 42
	s_add_i32 s3, 0, 0x23fc4
	v_writelane_b32 v255, s3, 43
	v_cmp_eq_u32_e64 s[4:5], 0, v219
	s_lshl_b64 s[46:47], s[28:29], 13
	v_mbcnt_lo_u32_b32 v2, -1, 0
	v_writelane_b32 v255, s4, 44
	s_mul_i32 s44, s26, 0x8400
	s_mul_hi_i32 s45, s28, 0x1080
	v_writelane_b32 v255, s5, 45
	v_cmp_eq_u32_e64 s[4:5], 0, v1
	s_movk_i32 s50, 0x2000
	s_movk_i32 s30, 0x840
	v_writelane_b32 v255, s4, 46
	v_mov_b32_e32 v0, 0
	v_mov_b32_e32 v224, 0x358637bd
	v_writelane_b32 v255, s5, 47
	v_writelane_b32 v255, s46, 48
	v_mov_b32_e32 v213, 1
	v_mov_b32_e32 v227, 0x1080
	v_mov_b32_e32 v228, 0x3a000000
	v_mbcnt_hi_u32_b32 v229, -1, v2
	v_mov_b32_e32 v16, 0xff800000
	v_mov_b32_e32 v230, 0x80
	s_mov_b32 s21, 0x800000
	s_movk_i32 s42, 0x2800
	s_movk_i32 s31, 0x110
	s_mov_b32 s69, 0xa0000
	s_mov_b32 s34, 0xff800000
	s_movk_i32 s0, 0x1640
	s_mov_b32 s1, 0xb0000
	s_movk_i32 s22, 0x2c80
	s_mov_b32 s3, s24
	s_mov_b64 s[48:49], 0x80
	s_lshl_b64 s[52:53], s[28:29], 2
	s_mov_b32 s55, 0
	s_mov_b64 s[56:57], 0x80000
	s_mov_b64 s[58:59], 0x90000
	s_mov_b64 s[60:61], 0xa0000
	s_mov_b64 s[62:63], 0xb0000
	s_mov_b32 s66, 0x3e0293ee
	v_writelane_b32 v255, s47, 49
	s_branch .LBB0_16

; #define LAS __attribute__((address_space(3)))
; __device__ __forceinline__ unsigned xb_xcc_id() { return (unsigned)__builtin_amdgcn_s_getreg((3 << 11) | 20) & 0xFu; }
; __device__ __forceinline__ void xcd_barrier(const XcdBarrier& b) {
;     asm volatile("s_waitcnt vmcnt(0)" ::: "memory");
;     __syncthreads();
;     if (threadIdx.x == 0) {
;         unsigned* bar = b.bar;
;         __builtin_amdgcn_s_waitcnt(0);
;         unsigned nloc = b.st[0], nx = b.st[1];
;         if (nloc == 0u) { xcd_barrier_complete(bar, b.x, nloc, nx); b.st[0] = nloc; b.st[1] = nx; }
; __global__ void __launch_bounds__(512, 2) fwd_kernel(Args a) {
;     ...
;     for (int ph = a.ph_lo; ph < a.ph_hi; ++ph) {
;         ArgsP ap = (ArgsP)__builtin_amdgcn_kernarg_segment_ptr();
;         asm volatile("" : "+s"(ap));
;         run_phase(ap, lds, ph);
;         if (ph + 1 < a.ph_hi && ((ph + 1) % NPH_LAYER) != 10) { if (ph == a.ph_lo) { grid.sync(); (void)xcd_barrier_post((unsigned*)(ap->ws + WS_CTL), (volatile LAS unsigned*)(lds + XB_LDS_OFF)); } else { XcdBarrier bar; bar.bar = (unsigned*)(ap->ws + WS_CTL); bar.x = xb_xcc_id(); bar.st = (volatile LAS unsigned*)(lds + XB_LDS_OFF); xcd_barrier(bar); } }
;     }
.LBB0_511:
	s_add_i32 s3, s29, 1
	s_cmp_ge_i32 s3, s25
	s_mul_hi_i32 s6, s3, 0x92492493
	s_cselect_b64 s[4:5], -1, 0
	s_add_i32 s6, s6, s3
	s_lshr_b32 s7, s6, 31
	s_ashr_i32 s6, s6, 3
	s_add_i32 s6, s6, s7
	s_mul_i32 s6, s6, 14
	s_sub_i32 s6, s3, s6
	s_cmp_eq_u32 s6, 10
	s_cselect_b64 s[6:7], -1, 0
	s_or_b64 s[4:5], s[4:5], s[6:7]
	s_cmp_eq_u32 s3, 14
	s_cselect_b64 s[6:7], -1, 0
	s_or_b64 s[4:5], s[4:5], s[6:7]
	s_and_b64 vcc, exec, s[4:5]
	s_movk_i32 s31, 0x110
	v_readlane_b32 s46, v255, 48
	v_readlane_b32 s47, v255, 49
	s_cbranch_vccnz .LBB0_15
	s_cmp_lg_u32 s29, s24
	s_mov_b64 s[4:5], -1
	s_cbranch_scc0 .LBB0_566
	s_getreg_b32 s4, hwreg(HW_REG_XCC_ID, 0, 4)
	s_waitcnt vmcnt(0)
	s_waitcnt vmcnt(0)
	s_barrier
	s_mov_b64 s[6:7], exec
	v_readlane_b32 s8, v255, 44
	v_readlane_b32 s9, v255, 45
	s_and_b64 s[8:9], s[6:7], s[8:9]
	s_mov_b64 exec, s[8:9]
	s_cbranch_execz .LBB0_565
	v_readlane_b32 s5, v255, 42
	s_waitcnt vmcnt(0) expcnt(0) lgkmcnt(0)
	s_and_b32 s20, s4, 15
	v_mov_b32_e32 v1, s5
	ds_read_b32 v3, v1
	v_readlane_b32 s5, v255, 43
	s_waitcnt lgkmcnt(0)
	v_cmp_ne_u32_e32 vcc, 0, v3
	v_mov_b32_e32 v1, s5
	ds_read_b32 v2, v1
	s_cbranch_vccnz .LBB0_529
	s_add_u32 s4, s70, 0x27000200
	s_addc_u32 s5, s71, 0
	s_add_u32 s8, s70, 0x27000400
	s_addc_u32 s9, s71, 0
	s_add_u32 s10, s70, 0x27000500
	s_addc_u32 s11, s71, 0
	s_add_u32 s12, s70, 0x27000600
	s_addc_u32 s13, s71, 0
	s_add_u32 s14, s70, 0x27000700
	s_addc_u32 s15, s71, 0
	s_add_u32 s16, s70, 0x27000800
	s_addc_u32 s17, s71, 0
	s_add_u32 s18, s70, 0x27000900
	s_addc_u32 s19, s71, 0
	s_add_u32 s36, s70, 0x27000a00
	s_addc_u32 s37, s71, 0
	s_add_u32 s38, s70, 0x27000b00
	s_addc_u32 s39, s71, 0
	s_add_u32 s64, s70, 0x27000c00
	s_addc_u32 s65, s71, 0
	s_add_u32 s72, s70, 0x27000d00
	s_addc_u32 s73, s71, 0
	s_add_u32 s74, s70, 0x27000e00
	s_addc_u32 s75, s71, 0
	s_add_u32 s76, s70, 0x27000f00
	s_addc_u32 s77, s71, 0
	s_add_u32 s78, s70, 0x27001000
	s_addc_u32 s79, s71, 0
	s_add_u32 s80, s70, 0x27001100
	s_addc_u32 s81, s71, 0
	s_add_u32 s82, s70, 0x27001200
	s_addc_u32 s83, s71, 0
	s_add_u32 s84, s70, 0x27001300
	s_addc_u32 s85, s71, 0
	s_mov_b32 s23, 1
	s_branch .LBB0_517
